# P3 epilogue: x residual loads use nt policy (read once); plus P0 x loads nt
# speedup vs baseline: 1.0510x; 1.0168x over previous
.LBB0_385:
	v_mov_b32_e32 v140, v144
	s_lshl_b32 s9, s44, 8
	v_readfirstlane_b32 s8, v140
	s_bfe_u32 s29, s8, 0x20006
	s_ashr_i32 s8, s8, 2
	s_andn2_b32 s8, s8, 63
	s_add_i32 s8, s8, s9
	v_and_or_b32 v142, v140, 15, s8
	s_lshl_b32 s8, s20, 8
	s_lshl_b32 s9, s29, 6
	v_bfe_u32 v149, v140, 4, 2
	s_or_b32 s8, s9, s8
	v_lshl_or_b32 v140, v149, 3, s8
	v_ashrrev_i32_e32 v143, 31, v142
	v_ashrrev_i32_e32 v141, 31, v140
	v_lshlrev_b64 v[150:151], 10, v[142:143]
	v_lshl_add_u64 v[158:159], v[150:151], 0, v[140:141]
	v_lshl_add_u64 v[160:161], v[158:159], 2, s[12:13]
	global_load_dwordx4 v[150:153], v[160:161], off nt
	global_load_dwordx4 v[154:157], v[160:161], off offset:16 nt
	v_lshl_add_u64 v[158:159], v[158:159], 1, s[16:17]
	s_lshl_b32 s44, s20, 2
	v_cmp_eq_u32_e32 vcc, 0, v149
	s_ashr_i32 s45, s44, 31
	s_waitcnt vmcnt(0)
	v_pk_add_f32 v[152:153], v[126:127], v[152:153]
	v_pk_add_f32 v[150:151], v[124:125], v[150:151]
	v_pk_add_f32 v[156:157], v[122:123], v[156:157]
	v_pk_add_f32 v[154:155], v[120:121], v[154:155]
	v_cvt_pk_bf16_f32 v120, v150, v151
	v_cvt_pk_bf16_f32 v121, v152, v153
	v_cvt_pk_bf16_f32 v122, v154, v155
	v_cvt_pk_bf16_f32 v123, v156, v157
	global_store_dwordx4 v[158:159], v[120:123], off
	global_load_dwordx4 v[120:123], v[160:161], off offset:128 nt
	s_nop 0
	global_load_dwordx4 v[124:127], v[160:161], off offset:144 nt
	v_mul_f32_e32 v151, v151, v151
	v_mul_f32_e32 v153, v153, v153
	v_mul_f32_e32 v155, v155, v155
	v_mul_f32_e32 v157, v157, v157
	v_fmac_f32_e32 v151, v150, v150
	v_fmac_f32_e32 v153, v152, v152
	v_fmac_f32_e32 v155, v154, v154
	v_fmac_f32_e32 v157, v156, v156
	v_add_f32_e32 v150, v151, v153
	v_add_f32_e32 v151, v155, v157
	v_add_f32_e32 v150, v150, v151
	s_waitcnt vmcnt(1)
	v_pk_add_f32 v[118:119], v[118:119], v[122:123]
	v_pk_add_f32 v[116:117], v[116:117], v[120:121]
	s_waitcnt vmcnt(0)
	v_pk_add_f32 v[120:121], v[114:115], v[126:127]
	v_pk_add_f32 v[122:123], v[112:113], v[124:125]
	v_mul_f32_e32 v112, v117, v117
	v_mul_f32_e32 v113, v119, v119
	v_mul_f32_e32 v114, v123, v123
	v_mul_f32_e32 v115, v121, v121
	v_fmac_f32_e32 v112, v116, v116
	v_fmac_f32_e32 v113, v118, v118
	v_fmac_f32_e32 v114, v122, v122
	v_fmac_f32_e32 v115, v120, v120
	v_add_f32_e32 v112, v112, v113
	v_add_f32_e32 v113, v114, v115
	v_add_f32_e32 v112, v112, v113
	v_add_f32_e32 v112, v150, v112
	ds_bpermute_b32 v113, v193, v112
	v_cvt_pk_bf16_f32 v114, v116, v117
	v_cvt_pk_bf16_f32 v115, v118, v119
	v_cvt_pk_bf16_f32 v116, v122, v123
	v_cvt_pk_bf16_f32 v117, v120, v121
	s_waitcnt lgkmcnt(0)
	v_add_f32_e32 v112, v112, v113
	ds_bpermute_b32 v113, v194, v112
	global_store_dwordx4 v[158:159], v[114:117], off offset:64
	s_and_saveexec_b64 s[46:47], vcc
	s_cbranch_execz .LBB0_387
	v_lshlrev_b64 v[114:115], 6, v[142:143]
	v_lshl_add_u64 v[114:115], s[6:7], 0, v[114:115]
	v_lshl_add_u64 v[114:115], s[44:45], 2, v[114:115]
	s_lshl_b32 s20, s29, 2
	v_lshl_add_u64 v[114:115], v[114:115], 0, s[20:21]
	s_waitcnt lgkmcnt(0)
	v_add_f32_e32 v112, v112, v113
	global_store_dword v[114:115], v112, off
.LBB0_387:
	s_or_b64 exec, exec, s[46:47]
	v_or_b32_e32 v112, 16, v142
	s_waitcnt lgkmcnt(0)
	v_ashrrev_i32_e32 v113, 31, v112
	v_lshlrev_b64 v[114:115], 10, v[112:113]
	v_lshl_add_u64 v[122:123], v[114:115], 0, v[140:141]
	v_lshl_add_u64 v[124:125], v[122:123], 2, s[12:13]
	global_load_dwordx4 v[114:117], v[124:125], off nt
	global_load_dwordx4 v[118:121], v[124:125], off offset:16 nt
	v_lshl_add_u64 v[122:123], v[122:123], 1, s[16:17]
	s_waitcnt vmcnt(1)
	v_pk_add_f32 v[116:117], v[110:111], v[116:117]
	v_pk_add_f32 v[114:115], v[108:109], v[114:115]
	s_waitcnt vmcnt(0)
	v_pk_add_f32 v[120:121], v[106:107], v[120:121]
	v_pk_add_f32 v[118:119], v[104:105], v[118:119]
	v_cvt_pk_bf16_f32 v104, v114, v115
	v_cvt_pk_bf16_f32 v105, v116, v117
	v_cvt_pk_bf16_f32 v106, v118, v119
	v_cvt_pk_bf16_f32 v107, v120, v121
	global_store_dwordx4 v[122:123], v[104:107], off
	global_load_dwordx4 v[104:107], v[124:125], off offset:128 nt
	s_nop 0
	global_load_dwordx4 v[108:111], v[124:125], off offset:144 nt
	v_mul_f32_e32 v115, v115, v115
	v_mul_f32_e32 v117, v117, v117
	v_mul_f32_e32 v119, v119, v119
	v_mul_f32_e32 v121, v121, v121
	v_fmac_f32_e32 v115, v114, v114
	v_fmac_f32_e32 v117, v116, v116
	v_fmac_f32_e32 v119, v118, v118
	v_fmac_f32_e32 v121, v120, v120
	v_add_f32_e32 v114, v115, v117
	v_add_f32_e32 v115, v119, v121
	v_add_f32_e32 v114, v114, v115
	s_waitcnt vmcnt(1)
	v_pk_add_f32 v[102:103], v[102:103], v[106:107]
	v_pk_add_f32 v[100:101], v[100:101], v[104:105]
	s_waitcnt vmcnt(0)
	v_pk_add_f32 v[104:105], v[98:99], v[110:111]
	v_pk_add_f32 v[106:107], v[96:97], v[108:109]
	v_mul_f32_e32 v96, v101, v101
	v_mul_f32_e32 v97, v103, v103
	v_mul_f32_e32 v98, v107, v107
	v_mul_f32_e32 v99, v105, v105
	v_fmac_f32_e32 v96, v100, v100
	v_fmac_f32_e32 v97, v102, v102
	v_fmac_f32_e32 v98, v106, v106
	v_fmac_f32_e32 v99, v104, v104
	v_add_f32_e32 v96, v96, v97
	v_add_f32_e32 v97, v98, v99
	v_add_f32_e32 v96, v96, v97
	v_add_f32_e32 v96, v114, v96
	ds_bpermute_b32 v97, v193, v96
	v_cvt_pk_bf16_f32 v98, v100, v101
	v_cvt_pk_bf16_f32 v99, v102, v103
	v_cvt_pk_bf16_f32 v100, v106, v107
	v_cvt_pk_bf16_f32 v101, v104, v105
	s_waitcnt lgkmcnt(0)
	v_add_f32_e32 v96, v96, v97
	ds_bpermute_b32 v97, v194, v96
	global_store_dwordx4 v[122:123], v[98:101], off offset:64
	s_and_saveexec_b64 s[46:47], vcc
	s_cbranch_execz .LBB0_389
	v_lshlrev_b64 v[98:99], 6, v[112:113]
	v_lshl_add_u64 v[98:99], s[6:7], 0, v[98:99]
	v_lshl_add_u64 v[98:99], s[44:45], 2, v[98:99]
	s_lshl_b32 s20, s29, 2
	v_lshl_add_u64 v[98:99], v[98:99], 0, s[20:21]
	s_waitcnt lgkmcnt(0)
	v_add_f32_e32 v96, v96, v97
	global_store_dword v[98:99], v96, off
.LBB0_389:
	s_or_b64 exec, exec, s[46:47]
	v_or_b32_e32 v96, 32, v142
	s_waitcnt lgkmcnt(0)
	v_ashrrev_i32_e32 v97, 31, v96
	v_lshlrev_b64 v[98:99], 10, v[96:97]
	v_lshl_add_u64 v[106:107], v[98:99], 0, v[140:141]
	v_lshl_add_u64 v[108:109], v[106:107], 2, s[12:13]
	global_load_dwordx4 v[98:101], v[108:109], off nt
	global_load_dwordx4 v[102:105], v[108:109], off offset:16 nt
	v_lshl_add_u64 v[106:107], v[106:107], 1, s[16:17]
	s_waitcnt vmcnt(1)
	v_pk_add_f32 v[100:101], v[94:95], v[100:101]
	v_pk_add_f32 v[98:99], v[92:93], v[98:99]
	s_waitcnt vmcnt(0)
	v_pk_add_f32 v[104:105], v[90:91], v[104:105]
	v_pk_add_f32 v[102:103], v[88:89], v[102:103]
	v_cvt_pk_bf16_f32 v88, v98, v99
	v_cvt_pk_bf16_f32 v89, v100, v101
	v_cvt_pk_bf16_f32 v90, v102, v103
	v_cvt_pk_bf16_f32 v91, v104, v105
	global_store_dwordx4 v[106:107], v[88:91], off
	global_load_dwordx4 v[88:91], v[108:109], off offset:128 nt
	s_nop 0
	global_load_dwordx4 v[92:95], v[108:109], off offset:144 nt
	v_mul_f32_e32 v99, v99, v99
	v_mul_f32_e32 v101, v101, v101
	v_mul_f32_e32 v103, v103, v103
	v_mul_f32_e32 v105, v105, v105
	v_fmac_f32_e32 v99, v98, v98
	v_fmac_f32_e32 v101, v100, v100
	v_fmac_f32_e32 v103, v102, v102
	v_fmac_f32_e32 v105, v104, v104
	v_add_f32_e32 v98, v99, v101
	v_add_f32_e32 v99, v103, v105
	v_add_f32_e32 v98, v98, v99
	s_waitcnt vmcnt(1)
	v_pk_add_f32 v[86:87], v[86:87], v[90:91]
	v_pk_add_f32 v[84:85], v[84:85], v[88:89]
	s_waitcnt vmcnt(0)
	v_pk_add_f32 v[88:89], v[82:83], v[94:95]
	v_pk_add_f32 v[90:91], v[80:81], v[92:93]
	v_mul_f32_e32 v80, v85, v85
	v_mul_f32_e32 v81, v87, v87
	v_mul_f32_e32 v82, v91, v91
	v_mul_f32_e32 v83, v89, v89
	v_fmac_f32_e32 v80, v84, v84
	v_fmac_f32_e32 v81, v86, v86
	v_fmac_f32_e32 v82, v90, v90
	v_fmac_f32_e32 v83, v88, v88
	v_add_f32_e32 v80, v80, v81
	v_add_f32_e32 v81, v82, v83
	v_add_f32_e32 v80, v80, v81
	v_add_f32_e32 v80, v98, v80
	ds_bpermute_b32 v81, v193, v80
	v_cvt_pk_bf16_f32 v82, v84, v85
	v_cvt_pk_bf16_f32 v83, v86, v87
	v_cvt_pk_bf16_f32 v84, v90, v91
	v_cvt_pk_bf16_f32 v85, v88, v89
	s_waitcnt lgkmcnt(0)
	v_add_f32_e32 v80, v80, v81
	ds_bpermute_b32 v81, v194, v80
	global_store_dwordx4 v[106:107], v[82:85], off offset:64
	s_and_saveexec_b64 s[46:47], vcc
	s_cbranch_execz .LBB0_391
	v_lshlrev_b64 v[82:83], 6, v[96:97]
	v_lshl_add_u64 v[82:83], s[6:7], 0, v[82:83]
	v_lshl_add_u64 v[82:83], s[44:45], 2, v[82:83]
	s_lshl_b32 s20, s29, 2
	v_lshl_add_u64 v[82:83], v[82:83], 0, s[20:21]
	s_waitcnt lgkmcnt(0)
	v_add_f32_e32 v80, v80, v81
	global_store_dword v[82:83], v80, off
.LBB0_391:
	s_or_b64 exec, exec, s[46:47]
	v_or_b32_e32 v80, 48, v142
	s_waitcnt lgkmcnt(0)
	v_ashrrev_i32_e32 v81, 31, v80
	v_lshlrev_b64 v[82:83], 10, v[80:81]
	v_lshl_add_u64 v[90:91], v[82:83], 0, v[140:141]
	v_lshl_add_u64 v[92:93], v[90:91], 2, s[12:13]
	global_load_dwordx4 v[82:85], v[92:93], off nt
	global_load_dwordx4 v[86:89], v[92:93], off offset:16 nt
	v_lshl_add_u64 v[90:91], v[90:91], 1, s[16:17]
	s_waitcnt vmcnt(1)
	v_pk_add_f32 v[84:85], v[78:79], v[84:85]
	v_pk_add_f32 v[82:83], v[76:77], v[82:83]
	s_waitcnt vmcnt(0)
	v_pk_add_f32 v[88:89], v[74:75], v[88:89]
	v_pk_add_f32 v[86:87], v[72:73], v[86:87]
	v_cvt_pk_bf16_f32 v72, v82, v83
	v_cvt_pk_bf16_f32 v73, v84, v85
	v_cvt_pk_bf16_f32 v74, v86, v87
	v_cvt_pk_bf16_f32 v75, v88, v89
	global_store_dwordx4 v[90:91], v[72:75], off
	global_load_dwordx4 v[72:75], v[92:93], off offset:128 nt
	s_nop 0
	global_load_dwordx4 v[76:79], v[92:93], off offset:144 nt
	v_mul_f32_e32 v83, v83, v83
	v_mul_f32_e32 v85, v85, v85
	v_mul_f32_e32 v87, v87, v87
	v_mul_f32_e32 v89, v89, v89
	v_fmac_f32_e32 v83, v82, v82
	v_fmac_f32_e32 v85, v84, v84
	v_fmac_f32_e32 v87, v86, v86
	v_fmac_f32_e32 v89, v88, v88
	v_add_f32_e32 v82, v83, v85
	v_add_f32_e32 v83, v87, v89
	v_add_f32_e32 v82, v82, v83
	s_waitcnt vmcnt(1)
	v_pk_add_f32 v[70:71], v[70:71], v[74:75]
	v_pk_add_f32 v[68:69], v[68:69], v[72:73]
	s_waitcnt vmcnt(0)
	v_pk_add_f32 v[72:73], v[66:67], v[78:79]
	v_pk_add_f32 v[74:75], v[64:65], v[76:77]
	v_mul_f32_e32 v64, v69, v69
	v_mul_f32_e32 v65, v71, v71
	v_mul_f32_e32 v66, v75, v75
	v_mul_f32_e32 v67, v73, v73
	v_fmac_f32_e32 v64, v68, v68
	v_fmac_f32_e32 v65, v70, v70
	v_fmac_f32_e32 v66, v74, v74
	v_fmac_f32_e32 v67, v72, v72
	v_add_f32_e32 v64, v64, v65
	v_add_f32_e32 v65, v66, v67
	v_add_f32_e32 v64, v64, v65
	v_add_f32_e32 v64, v82, v64
	ds_bpermute_b32 v65, v193, v64
	v_cvt_pk_bf16_f32 v66, v68, v69
	v_cvt_pk_bf16_f32 v67, v70, v71
	v_cvt_pk_bf16_f32 v68, v74, v75
	v_cvt_pk_bf16_f32 v69, v72, v73
	s_waitcnt lgkmcnt(0)
	v_add_f32_e32 v64, v64, v65
	ds_bpermute_b32 v65, v194, v64
	global_store_dwordx4 v[90:91], v[66:69], off offset:64
	s_and_saveexec_b64 s[46:47], vcc
	s_cbranch_execz .LBB0_393
	v_lshlrev_b64 v[66:67], 6, v[80:81]
	v_lshl_add_u64 v[66:67], s[6:7], 0, v[66:67]
	v_lshl_add_u64 v[66:67], s[44:45], 2, v[66:67]
	s_lshl_b32 s20, s29, 2
	v_lshl_add_u64 v[66:67], v[66:67], 0, s[20:21]
	s_waitcnt lgkmcnt(0)
	v_add_f32_e32 v64, v64, v65
	global_store_dword v[66:67], v64, off
.LBB0_393:
	s_or_b64 exec, exec, s[46:47]
	v_add_u32_e32 v64, 0x80, v142
	s_waitcnt lgkmcnt(0)
	v_ashrrev_i32_e32 v65, 31, v64
	v_lshlrev_b64 v[66:67], 10, v[64:65]
	v_lshl_add_u64 v[74:75], v[66:67], 0, v[140:141]
	v_lshl_add_u64 v[76:77], v[74:75], 2, s[12:13]
	global_load_dwordx4 v[66:69], v[76:77], off nt
	global_load_dwordx4 v[70:73], v[76:77], off offset:16 nt
	v_lshl_add_u64 v[74:75], v[74:75], 1, s[16:17]
	s_waitcnt vmcnt(1)
	v_pk_add_f32 v[68:69], v[62:63], v[68:69]
	v_pk_add_f32 v[66:67], v[60:61], v[66:67]
	s_waitcnt vmcnt(0)
	v_pk_add_f32 v[72:73], v[58:59], v[72:73]
	v_pk_add_f32 v[70:71], v[56:57], v[70:71]
	v_cvt_pk_bf16_f32 v56, v66, v67
	v_cvt_pk_bf16_f32 v57, v68, v69
	v_cvt_pk_bf16_f32 v58, v70, v71
	v_cvt_pk_bf16_f32 v59, v72, v73
	global_store_dwordx4 v[74:75], v[56:59], off
	global_load_dwordx4 v[56:59], v[76:77], off offset:128 nt
	s_nop 0
	global_load_dwordx4 v[60:63], v[76:77], off offset:144 nt
	v_mul_f32_e32 v67, v67, v67
	v_mul_f32_e32 v69, v69, v69
	v_mul_f32_e32 v71, v71, v71
	v_mul_f32_e32 v73, v73, v73
	v_fmac_f32_e32 v67, v66, v66
	v_fmac_f32_e32 v69, v68, v68
	v_fmac_f32_e32 v71, v70, v70
	v_fmac_f32_e32 v73, v72, v72
	v_add_f32_e32 v66, v67, v69
	v_add_f32_e32 v67, v71, v73
	v_add_f32_e32 v66, v66, v67
	s_waitcnt vmcnt(1)
	v_pk_add_f32 v[54:55], v[54:55], v[58:59]
	v_pk_add_f32 v[52:53], v[52:53], v[56:57]
	s_waitcnt vmcnt(0)
	v_pk_add_f32 v[56:57], v[50:51], v[62:63]
	v_pk_add_f32 v[58:59], v[48:49], v[60:61]
	v_mul_f32_e32 v48, v53, v53
	v_mul_f32_e32 v49, v55, v55
	v_mul_f32_e32 v50, v59, v59
	v_mul_f32_e32 v51, v57, v57
	v_fmac_f32_e32 v48, v52, v52
	v_fmac_f32_e32 v49, v54, v54
	v_fmac_f32_e32 v50, v58, v58
	v_fmac_f32_e32 v51, v56, v56
	v_add_f32_e32 v48, v48, v49
	v_add_f32_e32 v49, v50, v51
	v_add_f32_e32 v48, v48, v49
	v_add_f32_e32 v48, v66, v48
	ds_bpermute_b32 v49, v193, v48
	v_cvt_pk_bf16_f32 v50, v52, v53
	v_cvt_pk_bf16_f32 v51, v54, v55
	v_cvt_pk_bf16_f32 v52, v58, v59
	v_cvt_pk_bf16_f32 v53, v56, v57
	s_waitcnt lgkmcnt(0)
	v_add_f32_e32 v48, v48, v49
	ds_bpermute_b32 v49, v194, v48
	global_store_dwordx4 v[74:75], v[50:53], off offset:64
	s_and_saveexec_b64 s[46:47], vcc
	s_cbranch_execz .LBB0_395
	v_lshlrev_b64 v[50:51], 6, v[64:65]
	v_lshl_add_u64 v[50:51], s[6:7], 0, v[50:51]
	v_lshl_add_u64 v[50:51], s[44:45], 2, v[50:51]
	s_lshl_b32 s20, s29, 2
	v_lshl_add_u64 v[50:51], v[50:51], 0, s[20:21]
	s_waitcnt lgkmcnt(0)
	v_add_f32_e32 v48, v48, v49
	global_store_dword v[50:51], v48, off
.LBB0_395:
	s_or_b64 exec, exec, s[46:47]
	v_add_u32_e32 v48, 0x90, v142
	s_waitcnt lgkmcnt(0)
	v_ashrrev_i32_e32 v49, 31, v48
	v_lshlrev_b64 v[50:51], 10, v[48:49]
	v_lshl_add_u64 v[58:59], v[50:51], 0, v[140:141]
	v_lshl_add_u64 v[60:61], v[58:59], 2, s[12:13]
	global_load_dwordx4 v[50:53], v[60:61], off nt
	global_load_dwordx4 v[54:57], v[60:61], off offset:16 nt
	v_lshl_add_u64 v[58:59], v[58:59], 1, s[16:17]
	s_waitcnt vmcnt(1)
	v_pk_add_f32 v[52:53], v[46:47], v[52:53]
	v_pk_add_f32 v[50:51], v[44:45], v[50:51]
	s_waitcnt vmcnt(0)
	v_pk_add_f32 v[56:57], v[42:43], v[56:57]
	v_pk_add_f32 v[54:55], v[40:41], v[54:55]
	v_cvt_pk_bf16_f32 v40, v50, v51
	v_cvt_pk_bf16_f32 v41, v52, v53
	v_cvt_pk_bf16_f32 v42, v54, v55
	v_cvt_pk_bf16_f32 v43, v56, v57
	global_store_dwordx4 v[58:59], v[40:43], off
	global_load_dwordx4 v[40:43], v[60:61], off offset:128 nt
	s_nop 0
	global_load_dwordx4 v[44:47], v[60:61], off offset:144 nt
	v_mul_f32_e32 v51, v51, v51
	v_mul_f32_e32 v53, v53, v53
	v_mul_f32_e32 v55, v55, v55
	v_mul_f32_e32 v57, v57, v57
	v_fmac_f32_e32 v51, v50, v50
	v_fmac_f32_e32 v53, v52, v52
	v_fmac_f32_e32 v55, v54, v54
	v_fmac_f32_e32 v57, v56, v56
	v_add_f32_e32 v50, v51, v53
	v_add_f32_e32 v51, v55, v57
	v_add_f32_e32 v50, v50, v51
	s_waitcnt vmcnt(1)
	v_pk_add_f32 v[38:39], v[38:39], v[42:43]
	v_pk_add_f32 v[36:37], v[36:37], v[40:41]
	s_waitcnt vmcnt(0)
	v_pk_add_f32 v[40:41], v[34:35], v[46:47]
	v_pk_add_f32 v[42:43], v[32:33], v[44:45]
	v_mul_f32_e32 v32, v37, v37
	v_mul_f32_e32 v33, v39, v39
	v_mul_f32_e32 v34, v43, v43
	v_mul_f32_e32 v35, v41, v41
	v_fmac_f32_e32 v32, v36, v36
	v_fmac_f32_e32 v33, v38, v38
	v_fmac_f32_e32 v34, v42, v42
	v_fmac_f32_e32 v35, v40, v40
	v_add_f32_e32 v32, v32, v33
	v_add_f32_e32 v33, v34, v35
	v_add_f32_e32 v32, v32, v33
	v_add_f32_e32 v32, v50, v32
	ds_bpermute_b32 v33, v193, v32
	v_cvt_pk_bf16_f32 v34, v36, v37
	v_cvt_pk_bf16_f32 v35, v38, v39
	v_cvt_pk_bf16_f32 v36, v42, v43
	v_cvt_pk_bf16_f32 v37, v40, v41
	s_waitcnt lgkmcnt(0)
	v_add_f32_e32 v32, v32, v33
	ds_bpermute_b32 v33, v194, v32
	global_store_dwordx4 v[58:59], v[34:37], off offset:64
	s_and_saveexec_b64 s[46:47], vcc
	s_cbranch_execz .LBB0_397
	v_lshlrev_b64 v[34:35], 6, v[48:49]
	v_lshl_add_u64 v[34:35], s[6:7], 0, v[34:35]
	v_lshl_add_u64 v[34:35], s[44:45], 2, v[34:35]
	s_lshl_b32 s20, s29, 2
	v_lshl_add_u64 v[34:35], v[34:35], 0, s[20:21]
	s_waitcnt lgkmcnt(0)
	v_add_f32_e32 v32, v32, v33
	global_store_dword v[34:35], v32, off
.LBB0_397:
	s_or_b64 exec, exec, s[46:47]
	v_add_u32_e32 v32, 0xa0, v142
	s_waitcnt lgkmcnt(0)
	v_ashrrev_i32_e32 v33, 31, v32
	v_lshlrev_b64 v[34:35], 10, v[32:33]
	v_lshl_add_u64 v[42:43], v[34:35], 0, v[140:141]
	v_lshl_add_u64 v[44:45], v[42:43], 2, s[12:13]
	global_load_dwordx4 v[34:37], v[44:45], off nt
	global_load_dwordx4 v[38:41], v[44:45], off offset:16 nt
	v_lshl_add_u64 v[42:43], v[42:43], 1, s[16:17]
	s_waitcnt vmcnt(1)
	v_pk_add_f32 v[36:37], v[30:31], v[36:37]
	v_pk_add_f32 v[34:35], v[28:29], v[34:35]
	s_waitcnt vmcnt(0)
	v_pk_add_f32 v[40:41], v[26:27], v[40:41]
	v_pk_add_f32 v[38:39], v[24:25], v[38:39]
	v_cvt_pk_bf16_f32 v24, v34, v35
	v_cvt_pk_bf16_f32 v25, v36, v37
	v_cvt_pk_bf16_f32 v26, v38, v39
	v_cvt_pk_bf16_f32 v27, v40, v41
	global_store_dwordx4 v[42:43], v[24:27], off
	global_load_dwordx4 v[24:27], v[44:45], off offset:128 nt
	s_nop 0
	global_load_dwordx4 v[28:31], v[44:45], off offset:144 nt
	v_mul_f32_e32 v35, v35, v35
	v_mul_f32_e32 v37, v37, v37
	v_mul_f32_e32 v39, v39, v39
	v_mul_f32_e32 v41, v41, v41
	v_fmac_f32_e32 v35, v34, v34
	v_fmac_f32_e32 v37, v36, v36
	v_fmac_f32_e32 v39, v38, v38
	v_fmac_f32_e32 v41, v40, v40
	v_add_f32_e32 v34, v35, v37
	v_add_f32_e32 v35, v39, v41
	v_add_f32_e32 v34, v34, v35
	s_waitcnt vmcnt(1)
	v_pk_add_f32 v[22:23], v[22:23], v[26:27]
	v_pk_add_f32 v[20:21], v[20:21], v[24:25]
	s_waitcnt vmcnt(0)
	v_pk_add_f32 v[24:25], v[18:19], v[30:31]
	v_pk_add_f32 v[26:27], v[16:17], v[28:29]
	v_mul_f32_e32 v16, v21, v21
	v_mul_f32_e32 v17, v23, v23
	v_mul_f32_e32 v18, v27, v27
	v_mul_f32_e32 v19, v25, v25
	v_fmac_f32_e32 v16, v20, v20
	v_fmac_f32_e32 v17, v22, v22
	v_fmac_f32_e32 v18, v26, v26
	v_fmac_f32_e32 v19, v24, v24
	v_add_f32_e32 v16, v16, v17
	v_add_f32_e32 v17, v18, v19
	v_add_f32_e32 v16, v16, v17
	v_add_f32_e32 v16, v34, v16
	ds_bpermute_b32 v17, v193, v16
	v_cvt_pk_bf16_f32 v18, v20, v21
	v_cvt_pk_bf16_f32 v19, v22, v23
	v_cvt_pk_bf16_f32 v20, v26, v27
	v_cvt_pk_bf16_f32 v21, v24, v25
	s_waitcnt lgkmcnt(0)
	v_add_f32_e32 v16, v16, v17
	ds_bpermute_b32 v17, v194, v16
	global_store_dwordx4 v[42:43], v[18:21], off offset:64
	s_and_saveexec_b64 s[46:47], vcc
	s_cbranch_execz .LBB0_399
	v_lshlrev_b64 v[18:19], 6, v[32:33]
	v_lshl_add_u64 v[18:19], s[6:7], 0, v[18:19]
	v_lshl_add_u64 v[18:19], s[44:45], 2, v[18:19]
	s_lshl_b32 s20, s29, 2
	v_lshl_add_u64 v[18:19], v[18:19], 0, s[20:21]
	s_waitcnt lgkmcnt(0)
	v_add_f32_e32 v16, v16, v17
	global_store_dword v[18:19], v16, off
.LBB0_399:
	s_or_b64 exec, exec, s[46:47]
	v_add_u32_e32 v16, 0xb0, v142
	s_waitcnt lgkmcnt(0)
	v_ashrrev_i32_e32 v17, 31, v16
	v_lshlrev_b64 v[18:19], 10, v[16:17]
	v_lshl_add_u64 v[26:27], v[18:19], 0, v[140:141]
	v_lshl_add_u64 v[28:29], v[26:27], 2, s[12:13]
	global_load_dwordx4 v[18:21], v[28:29], off nt
	global_load_dwordx4 v[22:25], v[28:29], off offset:16 nt
	v_lshl_add_u64 v[26:27], v[26:27], 1, s[16:17]
	s_waitcnt vmcnt(1)
	v_pk_add_f32 v[20:21], v[14:15], v[20:21]
	v_pk_add_f32 v[18:19], v[12:13], v[18:19]
	s_waitcnt vmcnt(0)
	v_pk_add_f32 v[24:25], v[10:11], v[24:25]
	v_pk_add_f32 v[22:23], v[8:9], v[22:23]
	v_cvt_pk_bf16_f32 v8, v18, v19
	v_cvt_pk_bf16_f32 v9, v20, v21
	v_cvt_pk_bf16_f32 v10, v22, v23
	v_cvt_pk_bf16_f32 v11, v24, v25
	global_store_dwordx4 v[26:27], v[8:11], off
	global_load_dwordx4 v[8:11], v[28:29], off offset:128 nt
	s_nop 0
	global_load_dwordx4 v[12:15], v[28:29], off offset:144 nt
	v_mul_f32_e32 v19, v19, v19
	v_mul_f32_e32 v21, v21, v21
	v_mul_f32_e32 v23, v23, v23
	v_mul_f32_e32 v25, v25, v25
	v_fmac_f32_e32 v19, v18, v18
	v_fmac_f32_e32 v21, v20, v20
	v_fmac_f32_e32 v23, v22, v22
	v_fmac_f32_e32 v25, v24, v24
	v_add_f32_e32 v18, v19, v21
	v_add_f32_e32 v19, v23, v25
	v_add_f32_e32 v18, v18, v19
	s_waitcnt vmcnt(1)
	v_pk_add_f32 v[6:7], v[6:7], v[10:11]
	v_pk_add_f32 v[4:5], v[4:5], v[8:9]
	s_waitcnt vmcnt(0)
	v_pk_add_f32 v[8:9], v[2:3], v[14:15]
	v_pk_add_f32 v[10:11], v[0:1], v[12:13]
	v_mul_f32_e32 v0, v5, v5
	v_mul_f32_e32 v1, v7, v7
	v_mul_f32_e32 v2, v11, v11
	v_mul_f32_e32 v3, v9, v9
	v_fmac_f32_e32 v0, v4, v4
	v_fmac_f32_e32 v1, v6, v6
	v_fmac_f32_e32 v2, v10, v10
	v_fmac_f32_e32 v3, v8, v8
	v_add_f32_e32 v0, v0, v1
	v_add_f32_e32 v1, v2, v3
	v_add_f32_e32 v0, v0, v1
	v_add_f32_e32 v0, v18, v0
	ds_bpermute_b32 v1, v193, v0
	v_cvt_pk_bf16_f32 v2, v4, v5
	v_cvt_pk_bf16_f32 v3, v6, v7
	v_cvt_pk_bf16_f32 v4, v10, v11
	v_cvt_pk_bf16_f32 v5, v8, v9
	s_waitcnt lgkmcnt(0)
	v_add_f32_e32 v0, v0, v1
	ds_bpermute_b32 v1, v194, v0
	global_store_dwordx4 v[26:27], v[2:5], off offset:64
	s_and_saveexec_b64 s[46:47], vcc
	s_cbranch_execz .LBB0_401
	v_lshlrev_b64 v[2:3], 6, v[16:17]
	v_lshl_add_u64 v[2:3], s[6:7], 0, v[2:3]
	v_lshl_add_u64 v[2:3], s[44:45], 2, v[2:3]
	s_lshl_b32 s20, s29, 2
	v_lshl_add_u64 v[2:3], v[2:3], 0, s[20:21]
	s_waitcnt lgkmcnt(0)
	v_add_f32_e32 v0, v0, v1
	global_store_dword v[2:3], v0, off
